# added: fill_rstd reuses the previous unit's rstd when the row block repeats (skips reload)
# baseline (speedup 1.0000x reference)
.LBB0_200:
	s_or_b64 exec, exec, s[6:7]
	s_and_b64 s[2:3], s[4:5], exec
	s_cselect_b32 s9, 0, s52
	s_cmp_eq_u32 s9, 1
	s_cselect_b64 s[4:5], -1, 0
	s_and_b64 s[2:3], s[4:5], exec
	s_cselect_b32 s0, 13, 6
	s_cmp_eq_u32 s9, 0
	s_cselect_b64 s[6:7], -1, 0
	s_and_b64 s[2:3], s[6:7], exec
	s_mul_i32 s2, s52, 0x180000
	s_mov_b32 s3, s1
	v_writelane_b32 v255, s2, 4
	s_cselect_b32 s25, 12, s0
	s_mov_b32 s8, 0
	s_mov_b32 s12, 0
	v_writelane_b32 v255, s3, 5
	s_mov_b32 s24, 0
	s_mov_b32 s16, 0
	s_mov_b32 s3, 0
	s_mov_b32 s2, 0
	s_mov_b32 s30, s1
	v_and_b32_e32 v0, 0xff, v195
	v_lshrrev_b32_e32 v251, 8, v195
	s_movk_i32 s10, 0x100
	s_lshl_b32 s0, s25, 7
	s_nop 0
	v_cmp_gt_i32_e32 vcc, s10, v0
	s_and_saveexec_b64 s[10:11], vcc
	s_cbranch_execz .LBB0_205
	s_ashr_i32 s13, s12, 31
	s_add_u32 s14, s62, s12
	s_addc_u32 s15, s63, s13
	v_readlane_b32 s12, v255, 4
	v_readlane_b32 s13, v255, 5
	s_lshl_b64 s[12:13], s[12:13], 2
	s_add_u32 s12, s14, s12
	s_addc_u32 s13, s15, s13
	s_lshl_b32 s17, s25, 3
	s_abs_i32 s18, s17
	v_cvt_f32_u32_e32 v2, s18
	s_sub_i32 s14, 0, s18
	s_lshl_b32 s19, s25, 4
	s_bfe_i32 s26, s25, 0x1001c
	v_rcp_iflag_f32_e32 v3, v2
	v_mov_b32_e32 v2, 0x20400
	v_lshl_add_u32 v2, v0, 2, v2
	v_lshl_add_u32 v2, v251, 10, v2
	v_mul_f32_e32 v3, 0x4f7ffffe, v3
	v_cvt_u32_f32_e32 v3, v3
	s_nop 0
	v_readfirstlane_b32 s15, v3
	s_mul_i32 s14, s14, s15
	s_mul_hi_u32 s14, s15, s14
	s_add_i32 s28, s15, s14
	s_mov_b64 s[14:15], s[88:89]
	v_readfirstlane_b32 s100, v251
	s_mul_i32 s100, s100, s94
	s_add_u32 s14, s14, s100
	s_addc_u32 s15, s15, 0
	s_mov_b32 s101, -1
	s_branch .LBB0_203

.LBB0_203:
	v_mov_b64_e32 v[4:5], s[0:1]
	v_cmp_ge_i64_e32 vcc, s[14:15], v[4:5]
	s_mov_b64 s[20:21], -1
	s_cbranch_vccnz .LBB0_202
	s_ashr_i32 s20, s14, 31
	s_lshr_b32 s20, s20, 29
	s_add_i32 s20, s14, s20
	s_ashr_i32 s21, s20, 3
	s_and_b32 s20, s20, -8
	s_sub_i32 s20, s14, s20
	s_lshr_b32 s29, s20, 31
	s_or_b32 s29, s19, s29
	s_mul_i32 s20, s29, s20
	s_add_i32 s20, s20, s21
	s_abs_i32 s29, s20
	s_mul_hi_u32 s31, s29, s28
	s_mul_i32 s34, s31, s18
	s_ashr_i32 s21, s20, 31
	s_sub_i32 s29, s29, s34
	s_xor_b32 s21, s21, s26
	s_add_i32 s34, s31, 1
	s_sub_i32 s35, s29, s18
	s_cmp_ge_u32 s29, s18
	s_cselect_b32 s31, s34, s31
	s_cselect_b32 s29, s35, s29
	s_add_i32 s34, s31, 1
	s_cmp_ge_u32 s29, s18
	s_cselect_b32 s29, s34, s31
	s_xor_b32 s29, s29, s21
	s_sub_i32 s21, s29, s21
	s_lshl_b32 s29, s21, 3
	s_sub_i32 s31, 0x80, s29
	s_min_i32 s31, s31, 8
	s_abs_i32 s31, s31
	v_cvt_f32_u32_e32 v3, s31
	s_sub_i32 s34, 0, s31
	s_mul_i32 s21, s21, s17
	s_sub_i32 s20, s20, s21
	v_rcp_iflag_f32_e32 v3, v3
	s_ashr_i32 s21, s20, 31
	s_abs_i32 s20, s20
	v_mul_f32_e32 v3, 0x4f7ffffe, v3
	v_cvt_u32_f32_e32 v3, v3
	s_nop 0
	v_readfirstlane_b32 s35, v3
	s_mul_i32 s34, s34, s35
	s_mul_hi_u32 s34, s35, s34
	s_add_i32 s35, s35, s34
	s_mul_hi_u32 s34, s20, s35
	s_mul_i32 s34, s34, s31
	s_sub_i32 s20, s20, s34
	s_sub_i32 s34, s20, s31
	s_cmp_ge_u32 s20, s31
	s_cselect_b32 s20, s34, s20
	s_sub_i32 s34, s20, s31
	s_cmp_ge_u32 s20, s31
	s_cselect_b32 s20, s34, s20
	s_xor_b32 s20, s20, s21
	s_sub_i32 s20, s20, s21
	s_add_i32 s20, s20, s29
	s_cmp_eq_u32 s20, s101
	s_cselect_b32 s100, 1, 0
	s_mov_b32 s101, s20
	s_cbranch_scc1 .Lfr_a_0
	v_lshl_add_u32 v4, s20, 8, v0
	v_ashrrev_i32_e32 v5, 31, v4
	v_lshlrev_b64 v[4:5], 6, v[4:5]
	s_waitcnt vmcnt(1)
	v_lshl_add_u64 v[16:17], s[12:13], 0, v[4:5]
	global_load_dwordx4 v[4:7], v[16:17], off
	global_load_dwordx4 v[8:11], v[16:17], off offset:32
	global_load_dwordx4 v[12:15], v[16:17], off offset:16
	s_nop 0
	global_load_dwordx4 v[16:19], v[16:17], off offset:48
.Lfr_a_0:
	s_add_u32 s14, s14, s94
	s_addc_u32 s15, s15, s77
	s_add_u32 s14, s14, s94
	s_addc_u32 s15, s15, s77
	s_mov_b64 s[20:21], 0
	s_cmp_lg_u32 s100, 0
	s_cbranch_scc1 .Lfr_b_0
	s_waitcnt vmcnt(3)
	v_mov_b32_e32 v20, v4
	s_waitcnt vmcnt(2)
	v_mov_b32_e32 v21, v8
	v_mov_b32_e32 v8, v5
	v_mov_b32_e32 v4, v6
	v_mov_b32_e32 v5, v10
	v_mov_b32_e32 v10, v7
	s_waitcnt vmcnt(1)
	v_mov_b32_e32 v6, v12
	s_waitcnt vmcnt(0)
	v_mov_b32_e32 v7, v16
	v_mov_b32_e32 v16, v13
	v_mov_b32_e32 v12, v14
	v_mov_b32_e32 v13, v18
	v_mov_b32_e32 v18, v15
	v_pk_add_f32 v[8:9], v[20:21], v[8:9]
	v_pk_add_f32 v[4:5], v[4:5], v[10:11]
	v_pk_add_f32 v[6:7], v[6:7], v[16:17]
	v_pk_add_f32 v[10:11], v[12:13], v[18:19]
	v_pk_add_f32 v[4:5], v[8:9], v[4:5]
	v_pk_add_f32 v[6:7], v[6:7], v[10:11]
	s_nop 0
	v_pk_add_f32 v[4:5], v[4:5], v[6:7]
	s_nop 0
	v_add_f32_e32 v3, v4, v5
	v_mov_b32_e32 v4, 0x358637bd
	v_fmamk_f32 v3, v3, 0x3a800000, v4
	v_mul_f32_e32 v4, 0x4b800000, v3
	v_cmp_gt_f32_e32 vcc, s97, v3
	s_nop 1
	v_cndmask_b32_e32 v3, v3, v4, vcc
	v_rsq_f32_e32 v3, v3
	s_nop 0
	v_mul_f32_e32 v4, 0x45800000, v3
	v_cndmask_b32_e32 v3, v3, v4, vcc
	v_mov_b32_e32 v22, v3
.Lfr_b_0:
	ds_write_b32 v2, v22
	v_add_u32_e32 v2, 0x800, v2
	s_branch .LBB0_202

.LBB0_770:
	s_or_b64 exec, exec, s[6:7]
	s_mov_b32 s2, 0
	s_mov_b32 s0, 0
	s_mov_b32 s12, s1
	v_and_b32_e32 v0, 0xff, v195
	v_lshrrev_b32_e32 v251, 8, v195
	s_movk_i32 s3, 0x100
	s_waitcnt lgkmcnt(0)
	s_barrier
	s_nop 0
	v_cmp_gt_i32_e32 vcc, s3, v0
	s_and_saveexec_b64 s[6:7], vcc
	s_cbranch_execz .LBB0_779
	s_ashr_i32 s3, s0, 31
	s_add_u32 s0, s62, s0
	s_addc_u32 s3, s63, s3
	s_lshl_b64 s[4:5], s[4:5], 2
	s_add_u32 s4, s0, s4
	v_mov_b32_e32 v2, 0x20400
	s_addc_u32 s5, s3, s5
	v_lshl_add_u32 v2, v0, 2, v2
	v_lshl_add_u32 v2, v251, 10, v2
	s_mov_b64 s[8:9], s[88:89]
	v_readfirstlane_b32 s100, v251
	s_mul_i32 s100, s100, s94
	s_add_u32 s8, s8, s100
	s_addc_u32 s9, s9, 0
	s_mov_b32 s101, -1
	s_branch .LBB0_774
.LBB0_772:
	s_ashr_i32 s0, s0, 3
	s_add_i32 s0, s13, s0
	s_ashr_i32 s3, s0, 31
	s_lshr_b32 s3, s3, 25
	s_add_i32 s3, s0, s3
	s_ashr_i32 s10, s3, 7
	s_lshl_b32 s10, s10, 3
	s_sub_i32 s11, 0x80, s10
	s_min_i32 s11, s11, 8
	s_abs_i32 s11, s11
	v_cvt_f32_u32_e32 v3, s11
	s_sub_i32 s13, 0, s11
	s_and_b32 s3, s3, 0xffffff80
	s_sub_i32 s0, s0, s3
	v_rcp_iflag_f32_e32 v3, v3
	s_ashr_i32 s3, s0, 31
	s_abs_i32 s0, s0
	v_mul_f32_e32 v3, 0x4f7ffffe, v3
	v_cvt_u32_f32_e32 v3, v3
	s_nop 0
	v_readfirstlane_b32 s14, v3
	s_mul_i32 s13, s13, s14
	s_mul_hi_u32 s13, s14, s13
	s_add_i32 s14, s14, s13
	s_mul_hi_u32 s13, s0, s14
	s_mul_i32 s13, s13, s11
	s_sub_i32 s0, s0, s13
	s_sub_i32 s13, s0, s11
	s_cmp_ge_u32 s0, s11
	s_cselect_b32 s0, s13, s0
	s_sub_i32 s13, s0, s11
	s_cmp_ge_u32 s0, s11
	s_cselect_b32 s0, s13, s0
	s_xor_b32 s0, s0, s3
	s_sub_i32 s0, s0, s3
	s_add_i32 s10, s10, s0
	s_cmp_eq_u32 s10, s101
	s_cselect_b32 s100, 1, 0
	s_mov_b32 s101, s10
	s_cbranch_scc1 .Lfr_a_1
	v_lshl_add_u32 v4, s10, 8, v0
	v_ashrrev_i32_e32 v5, 31, v4
	v_lshlrev_b64 v[4:5], 6, v[4:5]
	v_lshl_add_u64 v[16:17], s[4:5], 0, v[4:5]
	global_load_dwordx4 v[4:7], v[16:17], off
	global_load_dwordx4 v[8:11], v[16:17], off offset:32
	global_load_dwordx4 v[12:15], v[16:17], off offset:16
	s_nop 0
	global_load_dwordx4 v[16:19], v[16:17], off offset:48
.Lfr_a_1:
	s_add_u32 s8, s8, s94
	s_addc_u32 s9, s9, s77
	s_add_u32 s8, s8, s94
	s_addc_u32 s9, s9, s77
	s_mov_b64 s[10:11], 0
	s_cmp_lg_u32 s100, 0
	s_cbranch_scc1 .Lfr_b_1
	s_waitcnt vmcnt(3)
	v_mov_b32_e32 v20, v4
	s_waitcnt vmcnt(2)
	v_mov_b32_e32 v21, v8
	v_mov_b32_e32 v8, v5
	v_mov_b32_e32 v4, v6
	v_mov_b32_e32 v5, v10
	v_mov_b32_e32 v10, v7
	s_waitcnt vmcnt(1)
	v_mov_b32_e32 v6, v12
	s_waitcnt vmcnt(0)
	v_mov_b32_e32 v7, v16
	v_mov_b32_e32 v16, v13
	v_mov_b32_e32 v12, v14
	v_mov_b32_e32 v13, v18
	v_mov_b32_e32 v18, v15
	v_pk_add_f32 v[8:9], v[20:21], v[8:9]
	v_pk_add_f32 v[4:5], v[4:5], v[10:11]
	v_pk_add_f32 v[6:7], v[6:7], v[16:17]
	v_pk_add_f32 v[10:11], v[12:13], v[18:19]
	v_pk_add_f32 v[4:5], v[8:9], v[4:5]
	v_pk_add_f32 v[6:7], v[6:7], v[10:11]
	s_nop 0
	v_pk_add_f32 v[4:5], v[4:5], v[6:7]
	s_nop 0
	v_add_f32_e32 v3, v4, v5
	v_mov_b32_e32 v4, 0x358637bd
	v_fmamk_f32 v3, v3, 0x3a800000, v4
	v_mul_f32_e32 v4, 0x4b800000, v3
	v_cmp_gt_f32_e32 vcc, s97, v3
	s_nop 1
	v_cndmask_b32_e32 v3, v3, v4, vcc
	v_rsq_f32_e32 v3, v3
	s_nop 0
	v_mul_f32_e32 v4, 0x45800000, v3
	v_cndmask_b32_e32 v3, v3, v4, vcc
	v_mov_b32_e32 v22, v3
.Lfr_b_1:
	ds_write_b32 v2, v22
	v_add_u32_e32 v2, 0x800, v2
